# LN2 (last phase) output stores write-through sc1 to avoid end-of-kernel L2 flush
# baseline (speedup 1.0000x reference)
; __device__ __forceinline__ f32x4 unpk4(u32x2 w) { f32x4 r; r.x = bflo(w.x); r.y = bfhi(w.x); r.z = bflo(w.y); r.w = bfhi(w.y); return r; }
; template <int WHICH, int NRW>
; __device__ __forceinline__ void ln_rows(const Params& p, const int row0, const int lane, const f32x4 (&gv)[4], const f32x4 (&bv)[4]) {
;     ...
;   for (int h = 0; h < NRW; ++h) {
;     const int row = row0 + h;
;     if (row < MP) {
;       const bf16_t* xr = (const bf16_t*)(p.ws + (WHICH == 1 ? OFF_PRE1 : OFF_PRE2)) + (size_t)row * DM;
; #pragma unroll
;       for (int j = 0; j < 4; ++j) v[h][j] = unpk4(*(const u32x2*)(xr + j * 256 + lane * 4));
;     } else {
;       const float* SL = (const float*)(p.ws + (WHICH == 1 ? OFF_SLAB_WO : OFF_SLAB_DN)) + (size_t)(row - MP) * DM;
;       constexpr int NS = (WHICH == 1) ? 8 : 11;
; #pragma unroll
;       for (int j = 0; j < 4; ++j) {
;         f32x4 a;
;         if (WHICH == 1) a = *(const f32x4*)(p.in[1] + (size_t)(row - MP) * DM + j * 256 + lane * 4) * ALPHA_F;
;         else a = unpk4(*(const u32x2*)(X1b + (size_t)row * DM + j * 256 + lane * 4)) * ALPHA_F;
; #pragma unroll
;         for (int q = 0; q < NS; ++q) a += *(const f32x4*)(SL + (size_t)q * MS * DM + j * 256 + lane * 4);
;         v[h][j] = a;
;       }
;     }
;   }
;   float s[NRW], s2[NRW];
; #pragma unroll
;   for (int h = 0; h < NRW; ++h) { s[h] = 0.f;
; #pragma unroll
;     for (int j = 0; j < 4; ++j) s[h] += (v[h][j].x + v[h][j].y) + (v[h][j].z + v[h][j].w); }
; #pragma unroll
;   for (int o = 1; o < 64; o <<= 1) {
; #pragma unroll
;     for (int h = 0; h < NRW; ++h) s[h] += __shfl_xor(s[h], o);
;   }
; #pragma unroll
;   for (int h = 0; h < NRW; ++h) { const float mean = s[h] * (1.f / DM); s2[h] = 0.f;
; #pragma unroll
;     for (int j = 0; j < 4; ++j) { v[h][j] = v[h][j] - mean; s2[h] += (v[h][j].x * v[h][j].x + v[h][j].y * v[h][j].y) + (v[h][j].z * v[h][j].z + v[h][j].w * v[h][j].w); } }
; #pragma unroll
;   for (int o = 1; o < 64; o <<= 1) {
; #pragma unroll
;     for (int h = 0; h < NRW; ++h) s2[h] += __shfl_xor(s2[h], o);
.LBB0_1312:
	v_ashrrev_i32_e32 v193, 31, v192
	v_lshlrev_b64 v[38:39], 11, v[192:193]
	v_lshl_add_u64 v[38:39], v[32:33], 0, v[38:39]
	global_load_dwordx2 v[40:41], v[38:39], off offset:1024
	global_load_dwordx2 v[42:43], v[38:39], off offset:1536
	global_load_dwordx2 v[44:45], v[38:39], off
	global_load_dwordx2 v[46:47], v[38:39], off offset:512
	v_add_u32_e32 v38, 1, v192
	v_ashrrev_i32_e32 v39, 31, v38
	v_lshlrev_b64 v[48:49], 11, v[38:39]
	v_lshl_add_u64 v[48:49], v[32:33], 0, v[48:49]
	global_load_dwordx2 v[50:51], v[48:49], off offset:1024
	global_load_dwordx2 v[64:65], v[48:49], off offset:1536
	global_load_dwordx2 v[66:67], v[48:49], off
	global_load_dwordx2 v[78:79], v[48:49], off offset:512
	v_lshlrev_b64 v[38:39], 12, v[38:39]
	v_add_u32_e32 v77, s66, v77
	s_waitcnt vmcnt(7)
	v_lshlrev_b32_e32 v60, 16, v40
	v_and_b32_e32 v61, 0xffff0000, v40
	s_waitcnt vmcnt(5)
	v_lshlrev_b32_e32 v69, 16, v45
	v_lshlrev_b32_e32 v68, 16, v44
	v_and_b32_e32 v81, 0xffff0000, v45
	v_and_b32_e32 v80, 0xffff0000, v44
	s_waitcnt vmcnt(4)
	v_lshlrev_b32_e32 v71, 16, v47
	v_lshlrev_b32_e32 v70, 16, v46
	v_and_b32_e32 v83, 0xffff0000, v47
	v_and_b32_e32 v82, 0xffff0000, v46
	v_pk_add_f32 v[84:85], v[68:69], v[80:81]
	v_pk_add_f32 v[86:87], v[70:71], v[82:83]
	v_lshlrev_b32_e32 v62, 16, v41
	v_and_b32_e32 v63, 0xffff0000, v41
	v_lshlrev_b32_e32 v59, 16, v42
	v_and_b32_e32 v55, 0xffff0000, v42
	v_add_f32_e32 v42, v84, v85
	v_pk_add_f32 v[84:85], v[86:87], v[86:87] op_sel:[0,1] op_sel_hi:[1,0]
	v_lshlrev_b32_e32 v57, 16, v43
	v_and_b32_e32 v53, 0xffff0000, v43
	v_add_f32_e32 v56, v60, v61
	v_add_f32_e32 v52, v62, v63
	v_add_f32_e32 v58, 0, v42
	v_mov_b32_e32 v85, v55
	s_waitcnt vmcnt(3)
	v_lshlrev_b32_e32 v48, 16, v50
	v_and_b32_e32 v49, 0xffff0000, v50
	v_lshlrev_b32_e32 v50, 16, v51
	v_and_b32_e32 v51, 0xffff0000, v51
	s_waitcnt vmcnt(2)
	v_lshlrev_b32_e32 v47, 16, v64
	v_and_b32_e32 v43, 0xffff0000, v64
	v_lshlrev_b32_e32 v45, 16, v65
	v_and_b32_e32 v41, 0xffff0000, v65
	s_waitcnt vmcnt(1)
	v_lshlrev_b32_e32 v65, 16, v67
	v_lshlrev_b32_e32 v64, 16, v66
	v_and_b32_e32 v89, 0xffff0000, v67
	v_and_b32_e32 v88, 0xffff0000, v66
	s_waitcnt vmcnt(0)
	v_lshlrev_b32_e32 v67, 16, v79
	v_lshlrev_b32_e32 v66, 16, v78
	v_and_b32_e32 v79, 0xffff0000, v79
	v_and_b32_e32 v78, 0xffff0000, v78
	v_pk_add_f32 v[86:87], v[56:57], v[52:53]
	v_pk_add_f32 v[84:85], v[58:59], v[84:85]
	v_pk_add_f32 v[90:91], v[64:65], v[88:89]
	v_pk_add_f32 v[92:93], v[66:67], v[78:79]
	v_add_f32_e32 v44, v48, v49
	v_add_f32_e32 v40, v50, v51
	v_pk_add_f32 v[84:85], v[84:85], v[86:87]
	v_add_f32_e32 v42, v90, v91
	v_pk_add_f32 v[90:91], v[92:93], v[92:93] op_sel:[0,1] op_sel_hi:[1,0]
	v_pk_add_f32 v[92:93], v[44:45], v[40:41]
	v_add_f32_e32 v40, v84, v85
	ds_bpermute_b32 v44, v37, v40
	v_add_f32_e32 v46, 0, v42
	v_mov_b32_e32 v91, v43
	v_pk_add_f32 v[86:87], v[46:47], v[90:91]
	s_waitcnt lgkmcnt(0)
	v_add_f32_e32 v40, v40, v44
	v_pk_add_f32 v[84:85], v[86:87], v[92:93]
	ds_bpermute_b32 v44, v72, v40
	v_add_f32_e32 v42, v84, v85
	ds_bpermute_b32 v46, v37, v42
	s_waitcnt lgkmcnt(1)
	v_add_f32_e32 v40, v40, v44
	ds_bpermute_b32 v44, v73, v40
	s_waitcnt lgkmcnt(1)
	v_add_f32_e32 v42, v42, v46
	ds_bpermute_b32 v46, v72, v42
	s_waitcnt lgkmcnt(1)
	v_add_f32_e32 v40, v40, v44
	ds_bpermute_b32 v44, v74, v40
	s_waitcnt lgkmcnt(1)
	v_add_f32_e32 v42, v42, v46
	ds_bpermute_b32 v46, v73, v42
	s_waitcnt lgkmcnt(1)
	v_add_f32_e32 v40, v40, v44
	ds_bpermute_b32 v44, v75, v40
	s_waitcnt lgkmcnt(1)
	v_add_f32_e32 v42, v42, v46
	ds_bpermute_b32 v46, v74, v42
	s_waitcnt lgkmcnt(1)
	v_add_f32_e32 v40, v40, v44
	ds_bpermute_b32 v44, v76, v40
	s_waitcnt lgkmcnt(1)
	v_add_f32_e32 v42, v42, v46
	ds_bpermute_b32 v46, v75, v42
	s_waitcnt lgkmcnt(1)
	v_add_f32_e32 v44, v40, v44
	v_fmac_f32_e32 v80, 0xba800000, v44
	s_waitcnt lgkmcnt(0)
	v_add_f32_e32 v42, v42, v46
	ds_bpermute_b32 v46, v76, v42
	v_fmac_f32_e32 v81, 0xba800000, v44
	v_fmac_f32_e32 v69, 0xba800000, v44
	v_fmac_f32_e32 v82, 0xba800000, v44
	v_fmac_f32_e32 v83, 0xba800000, v44
	v_fmac_f32_e32 v71, 0xba800000, v44
	v_fmac_f32_e32 v68, 0xba800000, v44
	v_fmac_f32_e32 v70, 0xba800000, v44
	v_mov_b32_e32 v84, v69
	v_mov_b32_e32 v85, v81
	v_mov_b32_e32 v69, v80
	v_mov_b32_e32 v86, v71
	v_mov_b32_e32 v87, v83
	v_mov_b32_e32 v71, v82
	v_pk_mul_f32 v[80:81], v[84:85], v[84:85]
	v_pk_mul_f32 v[82:83], v[68:69], v[68:69]
	v_pk_mul_f32 v[90:91], v[86:87], v[86:87]
	v_pk_mul_f32 v[92:93], v[70:71], v[70:71]
	v_fmac_f32_e32 v60, 0xba800000, v44
	v_fmac_f32_e32 v62, 0xba800000, v44
	v_pk_mov_b32 v[98:99], v[82:83], v[80:81] op_sel:[1,0]
	v_mov_b32_e32 v83, v81
	v_pk_mov_b32 v[80:81], v[92:93], v[90:91] op_sel:[1,0]
	v_mov_b32_e32 v93, v91
	s_waitcnt lgkmcnt(0)
; __device__ __forceinline__ u32x2 pk4(f32x4 v) { u32x2 r; r.x = pk2(v.x, v.y); r.y = pk2(v.z, v.w); return r; }
; template <int WHICH, int NRW>
; __device__ __forceinline__ void ln_rows(const Params& p, const int row0, const int lane, const f32x4 (&gv)[4], const f32x4 (&bv)[4]) {
;     ...
;   for (int h = 0; h < NRW; ++h) { const float mean = s[h] * (1.f / DM); s2[h] = 0.f;
; #pragma unroll
;     for (int j = 0; j < 4; ++j) { v[h][j] = v[h][j] - mean; s2[h] += (v[h][j].x * v[h][j].x + v[h][j].y * v[h][j].y) + (v[h][j].z * v[h][j].z + v[h][j].w * v[h][j].w); } }
; #pragma unroll
;   for (int o = 1; o < 64; o <<= 1) {
; #pragma unroll
;     for (int h = 0; h < NRW; ++h) s2[h] += __shfl_xor(s2[h], o);
;   }
; #pragma unroll
;   for (int h = 0; h < NRW; ++h) {
;     const int row = row0 + h;
;     const float rstd = rsqrtf(s2[h] * (1.f / DM) + LN_EPS_F);
; #pragma unroll
;     for (int j = 0; j < 4; ++j) {
;       const f32x4 o = v[h][j] * rstd * gv[j] + bv[j];
;       if (WHICH == 1) *(u32x2*)(X1b + (size_t)row * DM + j * 256 + lane * 4) = pk4(o);
;       else *(f32x4*)(p.out + (size_t)row * DM + j * 256 + lane * 4) = o;
;     }
;   }
	v_add_f32_e32 v46, v42, v46
	v_fmac_f32_e32 v61, 0xba800000, v44
	v_fmac_f32_e32 v63, 0xba800000, v44
	v_mul_f32_e32 v40, v60, v60
	v_mul_f32_e32 v42, v62, v62
	v_pk_add_f32 v[82:83], v[98:99], v[82:83]
	v_pk_add_f32 v[80:81], v[80:81], v[92:93]
	v_fmac_f32_e32 v53, 0xba800000, v44
	v_fmac_f32_e32 v57, 0xba800000, v44
	v_fmac_f32_e32 v55, 0xba800000, v44
	v_pk_fma_f32 v[94:95], v[60:61], v[60:61], v[40:41] op_sel_hi:[1,1,0]
	v_pk_fma_f32 v[96:97], v[62:63], v[62:63], v[42:43] op_sel_hi:[1,1,0]
	v_pk_add_f32 v[82:83], v[82:83], v[82:83] op_sel_hi:[0,1]
	v_pk_add_f32 v[80:81], v[80:81], v[80:81] op_sel_hi:[0,1]
	v_fmac_f32_e32 v59, 0xba800000, v44
	v_mul_f32_e32 v94, v59, v59
	v_mul_f32_e32 v96, v55, v55
	v_mul_f32_e32 v82, v57, v57
	v_mul_f32_e32 v80, v53, v53
	v_fmac_f32_e32 v88, 0xba800000, v46
	v_fmac_f32_e32 v89, 0xba800000, v46
	v_fmac_f32_e32 v65, 0xba800000, v46
	v_pk_add_f32 v[90:91], v[94:95], v[96:97]
	v_pk_add_f32 v[80:81], v[82:83], v[80:81]
	v_fmac_f32_e32 v64, 0xba800000, v46
	v_mov_b32_e32 v82, v65
	v_mov_b32_e32 v83, v89
	v_mov_b32_e32 v65, v88
	v_pk_add_f32 v[80:81], v[90:91], v[80:81]
	v_pk_mul_f32 v[90:91], v[82:83], v[82:83]
	v_pk_mul_f32 v[88:89], v[64:65], v[64:65]
	v_fmac_f32_e32 v78, 0xba800000, v46
	v_fmac_f32_e32 v79, 0xba800000, v46
	v_fmac_f32_e32 v67, 0xba800000, v46
	v_pk_mov_b32 v[92:93], v[88:89], v[90:91] op_sel:[1,0]
	v_mov_b32_e32 v89, v91
	v_fmac_f32_e32 v66, 0xba800000, v46
	v_mov_b32_e32 v90, v67
	v_mov_b32_e32 v91, v79
	v_mov_b32_e32 v67, v78
	v_pk_add_f32 v[88:89], v[92:93], v[88:89]
	v_pk_mul_f32 v[92:93], v[90:91], v[90:91]
	v_pk_mul_f32 v[78:79], v[66:67], v[66:67]
	v_fmac_f32_e32 v48, 0xba800000, v46
	v_pk_mov_b32 v[94:95], v[78:79], v[92:93] op_sel:[1,0]
	v_mov_b32_e32 v79, v93
	v_fmac_f32_e32 v49, 0xba800000, v46
	v_fmac_f32_e32 v50, 0xba800000, v46
	v_mul_f32_e32 v40, v48, v48
	v_pk_add_f32 v[78:79], v[94:95], v[78:79]
	v_fmac_f32_e32 v51, 0xba800000, v46
	v_pk_fma_f32 v[92:93], v[48:49], v[48:49], v[40:41] op_sel_hi:[1,1,0]
	v_mul_f32_e32 v40, v50, v50
	v_pk_add_f32 v[88:89], v[88:89], v[88:89] op_sel_hi:[0,1]
	v_pk_add_f32 v[78:79], v[78:79], v[78:79] op_sel_hi:[0,1]
	v_pk_fma_f32 v[94:95], v[50:51], v[50:51], v[40:41] op_sel_hi:[1,1,0]
	v_fmac_f32_e32 v41, 0xba800000, v46
	v_fmac_f32_e32 v45, 0xba800000, v46
	v_fmac_f32_e32 v43, 0xba800000, v46
	v_fmac_f32_e32 v47, 0xba800000, v46
	v_mul_f32_e32 v92, v47, v47
	v_mul_f32_e32 v94, v43, v43
	v_mul_f32_e32 v88, v45, v45
	v_mul_f32_e32 v78, v41, v41
	v_pk_add_f32 v[92:93], v[92:93], v[94:95]
	v_pk_add_f32 v[78:79], v[88:89], v[78:79]
	v_mov_b32_e32 v89, v80
	v_pk_add_f32 v[78:79], v[92:93], v[78:79]
	v_mov_b32_e32 v54, v59
	v_mov_b32_e32 v88, v78
	v_mov_b32_e32 v80, v79
	v_pk_add_f32 v[78:79], v[88:89], v[80:81]
	ds_bpermute_b32 v81, v37, v79
	ds_bpermute_b32 v80, v37, v78
	v_mov_b32_e32 v52, v57
	v_lshl_add_u64 v[56:57], v[34:35], 0, v[38:39]
	s_waitcnt lgkmcnt(0)
	v_pk_add_f32 v[78:79], v[78:79], v[80:81]
	ds_bpermute_b32 v81, v72, v79
	ds_bpermute_b32 v80, v72, v78
	s_waitcnt lgkmcnt(0)
	v_pk_add_f32 v[78:79], v[78:79], v[80:81]
	ds_bpermute_b32 v81, v73, v79
	ds_bpermute_b32 v80, v73, v78
	s_waitcnt lgkmcnt(0)
	v_pk_add_f32 v[78:79], v[78:79], v[80:81]
	ds_bpermute_b32 v81, v74, v79
	ds_bpermute_b32 v80, v74, v78
	s_waitcnt lgkmcnt(0)
	v_pk_add_f32 v[78:79], v[78:79], v[80:81]
	ds_bpermute_b32 v81, v75, v79
	ds_bpermute_b32 v80, v75, v78
	s_waitcnt lgkmcnt(0)
	v_pk_add_f32 v[78:79], v[78:79], v[80:81]
	ds_bpermute_b32 v81, v76, v79
	ds_bpermute_b32 v80, v76, v78
	s_waitcnt lgkmcnt(0)
	v_pk_add_f32 v[78:79], v[78:79], v[80:81]
	s_nop 0
	v_pk_fma_f32 v[88:89], v[78:79], s[6:7], v[36:37] op_sel_hi:[1,0,0]
	v_lshlrev_b64 v[78:79], 12, v[192:193]
	v_mul_f32_e32 v40, 0x4b800000, v89
	v_cmp_gt_f32_e32 vcc, s8, v89
	v_lshl_add_u64 v[92:93], v[34:35], 0, v[78:79]
	v_add_u32_e32 v192, s7, v192
	v_cndmask_b32_e32 v40, v89, v40, vcc
	v_rsq_f32_e32 v40, v40
	s_nop 0
	v_mul_f32_e32 v42, 0x45800000, v40
	v_cndmask_b32_e32 v40, v40, v42, vcc
	v_pk_mul_f32 v[68:69], v[68:69], v[40:41] op_sel_hi:[1,0]
	v_pk_mul_f32 v[78:79], v[84:85], v[40:41] op_sel_hi:[1,0]
	v_pk_mul_f32 v[60:61], v[60:61], v[40:41] op_sel_hi:[1,0]
	v_pk_fma_f32 v[80:81], v[2:3], v[78:79], v[6:7]
	v_pk_fma_f32 v[78:79], v[0:1], v[68:69], v[4:5]
	v_pk_mul_f32 v[68:69], v[70:71], v[40:41] op_sel_hi:[1,0]
	v_pk_mul_f32 v[70:71], v[86:87], v[40:41] op_sel_hi:[1,0]
	v_pk_mul_f32 v[62:63], v[62:63], v[40:41] op_sel_hi:[1,0]
	v_pk_mul_f32 v[58:59], v[54:55], v[40:41] op_sel_hi:[1,0]
	v_pk_mul_f32 v[52:53], v[52:53], v[40:41] op_sel_hi:[1,0]
	v_mul_f32_e32 v40, 0x4b800000, v88
	v_cmp_gt_f32_e32 vcc, s8, v88
	v_pk_fma_f32 v[54:55], v[26:27], v[52:53], v[30:31]
	v_pk_fma_f32 v[52:53], v[24:25], v[58:59], v[28:29]
	v_cndmask_b32_e32 v40, v88, v40, vcc
	v_rsq_f32_e32 v40, v40
	global_store_dwordx4 v[92:93], v[52:55], off offset:3072 sc1
	v_pk_fma_f32 v[70:71], v[10:11], v[70:71], v[14:15]
	v_pk_fma_f32 v[68:69], v[8:9], v[68:69], v[12:13]
	v_mul_f32_e32 v42, 0x45800000, v40
	v_cndmask_b32_e32 v44, v40, v42, vcc
	v_pk_mul_f32 v[52:53], v[64:65], v[44:45] op_sel_hi:[1,0]
	v_pk_mul_f32 v[54:55], v[82:83], v[44:45] op_sel_hi:[1,0]
	v_pk_fma_f32 v[52:53], v[0:1], v[52:53], v[4:5]
	v_pk_fma_f32 v[54:55], v[2:3], v[54:55], v[6:7]
	global_store_dwordx4 v[56:57], v[52:55], off sc1
	v_pk_mul_f32 v[38:39], v[66:67], v[44:45] op_sel_hi:[1,0]
	v_mov_b32_e32 v42, v47
	v_pk_mul_f32 v[52:53], v[90:91], v[44:45] op_sel_hi:[1,0]
	v_mov_b32_e32 v40, v45
	v_pk_fma_f32 v[54:55], v[10:11], v[52:53], v[14:15]
	v_pk_fma_f32 v[52:53], v[8:9], v[38:39], v[12:13]
	v_pk_mul_f32 v[38:39], v[48:49], v[44:45] op_sel_hi:[1,0]
	v_pk_mul_f32 v[48:49], v[50:51], v[44:45] op_sel_hi:[1,0]
	v_pk_mul_f32 v[40:41], v[40:41], v[44:45] op_sel_hi:[1,0]
	v_pk_fma_f32 v[50:51], v[18:19], v[48:49], v[22:23]
	v_pk_fma_f32 v[48:49], v[16:17], v[38:39], v[20:21]
	v_pk_mul_f32 v[38:39], v[42:43], v[44:45] op_sel_hi:[1,0]
	v_cmp_lt_i32_e32 vcc, s9, v77
	v_pk_fma_f32 v[62:63], v[18:19], v[62:63], v[22:23]
	v_pk_fma_f32 v[60:61], v[16:17], v[60:61], v[20:21]
	v_pk_fma_f32 v[40:41], v[26:27], v[40:41], v[30:31]
	v_pk_fma_f32 v[38:39], v[24:25], v[38:39], v[28:29]
	s_or_b64 s[4:5], vcc, s[4:5]
	global_store_dwordx4 v[92:93], v[78:81], off sc1
	global_store_dwordx4 v[92:93], v[68:71], off offset:1024 sc1
	global_store_dwordx4 v[92:93], v[60:63], off offset:2048 sc1
	global_store_dwordx4 v[56:57], v[52:55], off offset:1024 sc1
	global_store_dwordx4 v[56:57], v[48:51], off offset:2048 sc1
	global_store_dwordx4 v[56:57], v[38:41], off offset:3072 sc1
	s_andn2_b64 exec, exec, s[4:5]
	s_cbranch_execnz .LBB0_1312

; __device__ __forceinline__ u32x2 pk4(f32x4 v) { u32x2 r; r.x = pk2(v.x, v.y); r.y = pk2(v.z, v.w); return r; }
; template <int WHICH, int NRW>
; __device__ __forceinline__ void ln_rows(const Params& p, const int row0, const int lane, const f32x4 (&gv)[4], const f32x4 (&bv)[4]) {
;     ...
;   float s[NRW], s2[NRW];
; #pragma unroll
;   for (int h = 0; h < NRW; ++h) { s[h] = 0.f;
; #pragma unroll
;     for (int j = 0; j < 4; ++j) s[h] += (v[h][j].x + v[h][j].y) + (v[h][j].z + v[h][j].w); }
; #pragma unroll
;   for (int o = 1; o < 64; o <<= 1) {
; #pragma unroll
;     for (int h = 0; h < NRW; ++h) s[h] += __shfl_xor(s[h], o);
;   }
; #pragma unroll
;   for (int h = 0; h < NRW; ++h) { const float mean = s[h] * (1.f / DM); s2[h] = 0.f;
; #pragma unroll
;     for (int j = 0; j < 4; ++j) { v[h][j] = v[h][j] - mean; s2[h] += (v[h][j].x * v[h][j].x + v[h][j].y * v[h][j].y) + (v[h][j].z * v[h][j].z + v[h][j].w * v[h][j].w); } }
; #pragma unroll
;   for (int o = 1; o < 64; o <<= 1) {
; #pragma unroll
;     for (int h = 0; h < NRW; ++h) s2[h] += __shfl_xor(s2[h], o);
;   }
; #pragma unroll
;   for (int h = 0; h < NRW; ++h) {
;     const int row = row0 + h;
;     const float rstd = rsqrtf(s2[h] * (1.f / DM) + LN_EPS_F);
; #pragma unroll
;     for (int j = 0; j < 4; ++j) {
;       const f32x4 o = v[h][j] * rstd * gv[j] + bv[j];
;       if (WHICH == 1) *(u32x2*)(X1b + (size_t)row * DM + j * 256 + lane * 4) = pk4(o);
;       else *(f32x4*)(p.out + (size_t)row * DM + j * 256 + lane * 4) = o;
;     }
;   }
.LBB0_1315:
	s_or_b64 exec, exec, s[10:11]
	v_pk_add_f32 v[68:69], v[58:59], v[54:55]
	v_add_f32_e32 v43, v48, v49
	v_add_f32_e32 v41, v68, v69
	v_pk_add_f32 v[68:69], v[56:57], v[52:53]
	v_add_f32_e32 v47, 0, v41
	v_pk_add_f32 v[68:69], v[68:69], v[68:69] op_sel_hi:[0,1]
	v_add_f32_e32 v51, v44, v45
	v_mov_b32_e32 v41, v69
	v_pk_add_f32 v[70:71], v[42:43], v[50:51]
	v_pk_add_f32 v[68:69], v[40:41], v[46:47]
	v_add_u32_e32 v182, s66, v182
	v_pk_add_f32 v[68:69], v[70:71], v[68:69]
	v_lshl_add_u64 v[36:37], v[36:37], 0, s[0:1]
	v_add_f32_e32 v41, v68, v69
	ds_bpermute_b32 v43, v60, v41
	s_waitcnt lgkmcnt(0)
	v_add_f32_e32 v41, v41, v43
	ds_bpermute_b32 v43, v61, v41
	s_waitcnt lgkmcnt(0)
	v_add_f32_e32 v41, v41, v43
	ds_bpermute_b32 v43, v62, v41
	s_waitcnt lgkmcnt(0)
	v_add_f32_e32 v41, v41, v43
	ds_bpermute_b32 v43, v63, v41
	s_waitcnt lgkmcnt(0)
	v_add_f32_e32 v41, v41, v43
	ds_bpermute_b32 v43, v64, v41
	s_waitcnt lgkmcnt(0)
	v_add_f32_e32 v41, v41, v43
	ds_bpermute_b32 v43, v65, v41
	s_waitcnt lgkmcnt(0)
	v_add_f32_e32 v41, v41, v43
	v_fmac_f32_e32 v58, 0xba800000, v41
	v_fmac_f32_e32 v55, 0xba800000, v41
	v_fmac_f32_e32 v59, 0xba800000, v41
	v_fmac_f32_e32 v56, 0xba800000, v41
	v_fmac_f32_e32 v53, 0xba800000, v41
	v_fmac_f32_e32 v57, 0xba800000, v41
	v_fmac_f32_e32 v54, 0xba800000, v41
	v_fmac_f32_e32 v52, 0xba800000, v41
	v_mov_b32_e32 v68, v59
	v_mov_b32_e32 v69, v55
	v_mov_b32_e32 v55, v58
	v_mov_b32_e32 v58, v57
	v_mov_b32_e32 v59, v53
	v_mov_b32_e32 v53, v56
	v_pk_mul_f32 v[56:57], v[68:69], v[68:69]
	v_pk_mul_f32 v[70:71], v[54:55], v[54:55]
	v_pk_mul_f32 v[72:73], v[58:59], v[58:59]
	v_pk_mul_f32 v[74:75], v[52:53], v[52:53]
	v_pk_mov_b32 v[76:77], v[70:71], v[56:57] op_sel:[1,0]
	v_mov_b32_e32 v71, v57
	v_pk_mov_b32 v[56:57], v[74:75], v[72:73] op_sel:[1,0]
	v_mov_b32_e32 v75, v73
	v_pk_add_f32 v[56:57], v[56:57], v[74:75]
	v_fmac_f32_e32 v48, 0xba800000, v41
	v_pk_add_f32 v[56:57], v[56:57], v[56:57] op_sel_hi:[0,1]
	v_fmac_f32_e32 v49, 0xba800000, v41
	v_fmac_f32_e32 v44, 0xba800000, v41
	v_mul_f32_e32 v56, v48, v48
	v_pk_add_f32 v[70:71], v[76:77], v[70:71]
	v_fmac_f32_e32 v45, 0xba800000, v41
	v_pk_fma_f32 v[72:73], v[48:49], v[48:49], v[56:57] op_sel_hi:[1,1,0]
	v_mul_f32_e32 v56, v44, v44
	v_pk_add_f32 v[70:71], v[70:71], v[70:71] op_sel_hi:[0,1]
	v_pk_fma_f32 v[74:75], v[44:45], v[44:45], v[56:57] op_sel_hi:[1,1,0]
	v_fmac_f32_e32 v46, 0xba800000, v41
	v_fmac_f32_e32 v40, 0xba800000, v41
	v_fmac_f32_e32 v50, 0xba800000, v41
	v_fmac_f32_e32 v42, 0xba800000, v41
	v_mul_f32_e32 v72, v42, v42
	v_mul_f32_e32 v74, v50, v50
	v_mul_f32_e32 v70, v40, v40
	v_mul_f32_e32 v56, v46, v46
	v_pk_add_f32 v[72:73], v[72:73], v[74:75]
	v_pk_add_f32 v[56:57], v[70:71], v[56:57]
	s_nop 0
	v_pk_add_f32 v[56:57], v[72:73], v[56:57]
	s_nop 0
	v_add_f32_e32 v41, v56, v57
	ds_bpermute_b32 v43, v60, v41
	s_waitcnt lgkmcnt(0)
	v_add_f32_e32 v41, v41, v43
	ds_bpermute_b32 v43, v61, v41
	s_waitcnt lgkmcnt(0)
	v_add_f32_e32 v41, v41, v43
	ds_bpermute_b32 v43, v62, v41
	s_waitcnt lgkmcnt(0)
	v_add_f32_e32 v41, v41, v43
	ds_bpermute_b32 v43, v63, v41
	s_waitcnt lgkmcnt(0)
	v_add_f32_e32 v41, v41, v43
	ds_bpermute_b32 v43, v64, v41
	s_waitcnt lgkmcnt(0)
	v_add_f32_e32 v41, v41, v43
	ds_bpermute_b32 v43, v65, v41
	s_waitcnt lgkmcnt(0)
	v_add_f32_e32 v41, v41, v43
	v_fmamk_f32 v41, v41, 0x3a800000, v66
	v_mul_f32_e32 v43, 0x4b800000, v41
	v_cmp_gt_f32_e32 vcc, s12, v41
	s_nop 1
	v_cndmask_b32_e32 v41, v41, v43, vcc
	v_rsq_f32_e32 v41, v41
	s_nop 0
	v_mul_f32_e32 v43, 0x45800000, v41
	v_cndmask_b32_e32 v70, v41, v43, vcc
	v_pk_mul_f32 v[56:57], v[54:55], v[70:71] op_sel_hi:[1,0]
	v_pk_mul_f32 v[54:55], v[68:69], v[70:71] op_sel_hi:[1,0]
	v_pk_mul_f32 v[68:69], v[52:53], v[70:71] op_sel_hi:[1,0]
	v_pk_mul_f32 v[58:59], v[58:59], v[70:71] op_sel_hi:[1,0]
	s_waitcnt vmcnt(6)
	v_pk_fma_f32 v[54:55], v[2:3], v[54:55], v[6:7]
	v_pk_fma_f32 v[52:53], v[0:1], v[56:57], v[4:5]
	v_pk_mul_f32 v[44:45], v[44:45], v[70:71] op_sel_hi:[1,0]
	v_mov_b32_e32 v43, v50
	v_mov_b32_e32 v41, v46
	s_waitcnt vmcnt(4)
	v_pk_fma_f32 v[58:59], v[10:11], v[58:59], v[14:15]
	v_pk_fma_f32 v[56:57], v[8:9], v[68:69], v[12:13]
	global_store_dwordx4 v[38:39], v[52:55], off sc1
	global_store_dwordx4 v[38:39], v[56:59], off offset:1024 sc1
	v_pk_mul_f32 v[40:41], v[40:41], v[70:71] op_sel_hi:[1,0]
	s_waitcnt vmcnt(4)
	v_pk_fma_f32 v[54:55], v[18:19], v[44:45], v[22:23]
	v_pk_mul_f32 v[44:45], v[42:43], v[70:71] op_sel_hi:[1,0]
	s_waitcnt vmcnt(2)
	v_pk_fma_f32 v[42:43], v[26:27], v[40:41], v[30:31]
	v_pk_fma_f32 v[40:41], v[24:25], v[44:45], v[28:29]
	v_pk_mul_f32 v[48:49], v[48:49], v[70:71] op_sel_hi:[1,0]
	global_store_dwordx4 v[38:39], v[40:43], off offset:3072 sc1
	v_pk_fma_f32 v[52:53], v[16:17], v[48:49], v[20:21]
	global_store_dwordx4 v[38:39], v[52:55], off offset:2048 sc1
	v_add_u32_e32 v40, 0x4000, v182
	v_cmp_lt_i32_e32 vcc, s13, v40
	s_or_b64 s[6:7], vcc, s[6:7]
	v_lshl_add_u64 v[38:39], v[38:39], 0, s[4:5]
	s_andn2_b64 exec, exec, s[6:7]
	s_cbranch_execz .LBB0_1320
